# baseline (speedup 1.0000x reference)
; __device__ __forceinline__ bf16x8 gld16(const void* p) { bf16x8 v; asm volatile("global_load_dwordx4 %0, %1, off" : "=v"(v) : "v"(p) : "memory"); return v; }
;   __device__ __forceinline__ bfu* pb() const { return (bfu*)(b + L::o_pb); }
;   __device__ __forceinline__ float* gl() const { return (float*)(b + L::o_gl); }
; template <int BN, bool SWAP> ...
;     ...
;   const int lrow = tid >> 3, lch = (tid & 7) * 8;
;   const bfu* Ap = A + (size_t)lrow * lda + lch;
;   const bfu* Bp = B + (size_t)lrow * ldb + lch;
;   int brow = lrow;
;   if (SWAP) {
;     if (NJ == 4) brow = ((lrow & 12) << 2) | ((lrow >> 2) & 4) | (lrow & 3);
;     else brow = ((lrow & 4) << 2) | ((lrow >> 1) & 12) | (lrow & 3);
;   }
;   const int nk = K >> 6;
;   const bool chain = (An != nullptr);
;   const bfu* Apn = chain ? (An + (size_t)lrow * ldan + lch) : Ap;
;   const bfu* Bpn = chain ? (Bn + (size_t)lrow * ldbn + lch) : Bp;
;   auto gl = [&](bf16x8 (&ra)[4], bf16x8 (&rb)[NJ], int kt) {
;     const bool nx = (kt >= nk);
;     const bfu* pa = nx ? (chain ? Apn + (kt - nk) * 64 : Ap + (nk - 1) * 64) : Ap + kt * 64;
;     const bfu* pb = nx ? (chain ? Bpn + (kt - nk) * 64 : Bp + (nk - 1) * 64) : Bp + kt * 64;
;     const size_t sa = (nx && chain) ? (size_t)ldan : (size_t)lda, sb = (nx && chain) ? (size_t)ldbn : (size_t)ldb;
; #pragma unroll
;     for (int q = 0; q < 4; ++q) ra[q] = gld16(pa + (size_t)(32 * q) * sa);
; #pragma unroll
;     for (int q = 0; q < NJ; ++q) rb[q] = gld16(pb + (size_t)(32 * q) * sb);
;   };
;   auto wt = [&](bf16x8 (&ra)[4], bf16x8 (&rb)[NJ]) {
;     if (NJ == 4) asm volatile("s_waitcnt vmcnt(8)" : "+v"(ra[0]), "+v"(ra[1]), "+v"(ra[2]), "+v"(ra[3]), "+v"(rb[0]), "+v"(rb[1]), "+v"(rb[NJ - 2]), "+v"(rb[NJ - 1]) : : "memory");
;     else asm volatile("s_waitcnt vmcnt(6)" : "+v"(ra[0]), "+v"(ra[1]), "+v"(ra[2]), "+v"(ra[3]), "+v"(rb[0]), "+v"(rb[1]) : : "memory");
;   };
;   auto st = [&](const bf16x8 (&ra)[4], const bf16x8 (&rb)[NJ], int buf) {
; #pragma unroll
;     for (int q = 0; q < 4; ++q) *(bf16x8*)(As + (buf * 128 + lrow + 32 * q) * 72 + lch) = ra[q];
; #pragma unroll
;     for (int q = 0; q < NJ; ++q) *(bf16x8*)(Bs + (buf * BN + brow + ((SWAP && NJ == 4) ? (8 * (q & 1) + 64 * (q >> 1)) : 32 * q)) * 72 + lch) = rb[q];
;   };
;     ...
;   gl(ra0, rb0, 0);
;   gl(ra1, rb1, 1);
;   __syncthreads();
;   wt(ra0, rb0);
;   st(ra0, rb0, 0);
;   __syncthreads();
.LBB0_484:
	s_lshl_b32 s12, s14, 7
	s_lshl_b32 s14, s2, 7
	s_ashr_i32 s15, s14, 31
	s_lshl_b64 s[20:21], s[14:15], 11
	s_add_u32 s20, s70, s20
	s_addc_u32 s21, s71, s21
	s_ashr_i32 s13, s12, 31
	v_mov_b32_e32 v38, v174
	s_lshl_b64 s[22:23], s[12:13], 11
	s_add_u32 s22, s16, s22
	v_ashrrev_i32_e32 v32, 3, v38
	v_ashrrev_i32_e32 v33, 31, v32
	s_addc_u32 s23, s17, s23
	v_lshlrev_b64 v[0:1], 11, v[32:33]
	v_lshlrev_b32_e32 v4, 4, v38
	v_lshl_add_u64 v[2:3], s[20:21], 0, v[0:1]
	v_and_b32_e32 v152, 0x70, v4
	v_lshl_add_u64 v[0:1], s[22:23], 0, v[0:1]
	v_lshl_add_u64 v[100:101], v[0:1], 0, v[152:153]
	v_lshlrev_b32_e32 v0, 2, v32
	v_lshrrev_b32_e32 v1, 2, v32
	v_lshl_add_u64 v[98:99], v[2:3], 0, v[152:153]
	v_and_b32_e32 v0, 48, v0
	v_and_b32_e32 v1, 4, v1
	v_and_b32_e32 v2, 3, v32
	v_or3_b32 v33, v2, v1, v0
	global_load_dwordx4 v[0:3], v[98:99], off
	v_lshl_add_u64 v[4:5], v[98:99], 0, s[76:77]
	global_load_dwordx4 v[4:7], v[4:5], off
	v_lshl_add_u64 v[8:9], v[98:99], 0, s[8:9]
	global_load_dwordx4 v[8:11], v[8:9], off
	v_lshl_add_u64 v[12:13], v[98:99], 0, s[78:79]
	global_load_dwordx4 v[12:15], v[12:13], off
	global_load_dwordx4 v[16:19], v[100:101], off
	v_lshl_add_u64 v[20:21], v[100:101], 0, s[76:77]
	global_load_dwordx4 v[20:23], v[20:21], off
	v_lshl_add_u64 v[24:25], v[100:101], 0, s[8:9]
	global_load_dwordx4 v[24:27], v[24:25], off
	v_lshl_add_u64 v[28:29], v[100:101], 0, s[78:79]
	global_load_dwordx4 v[28:31], v[28:29], off
	v_lshl_add_u64 v[36:37], v[98:99], 0, s[80:81]
	global_load_dwordx4 v[40:43], v[36:37], off
	s_mov_b64 s[24:25], 0x10080
	v_lshl_add_u64 v[36:37], v[98:99], 0, s[24:25]
	global_load_dwordx4 v[44:47], v[36:37], off
	s_mov_b64 s[22:23], 0x20080
	v_lshl_add_u64 v[36:37], v[98:99], 0, s[22:23]
	global_load_dwordx4 v[48:51], v[36:37], off
	s_mov_b64 s[20:21], 0x30080
	v_lshl_add_u64 v[36:37], v[98:99], 0, s[20:21]
	global_load_dwordx4 v[52:55], v[36:37], off
	v_lshl_add_u64 v[34:35], v[100:101], 0, s[80:81]
	global_load_dwordx4 v[56:59], v[34:35], off
	v_lshl_add_u64 v[34:35], v[100:101], 0, s[24:25]
	global_load_dwordx4 v[60:63], v[34:35], off
	v_lshl_add_u64 v[34:35], v[100:101], 0, s[22:23]
	global_load_dwordx4 v[64:67], v[34:35], off
	v_lshl_add_u64 v[34:35], v[100:101], 0, s[20:21]
	global_load_dwordx4 v[72:75], v[34:35], off
	s_barrier
	s_waitcnt vmcnt(8)
	v_add_u32_e32 v140, 4, v32
	v_and_b32_e32 v140, 8, v140
	v_lshlrev_b32_e32 v140, 1, v140
	v_xor_b32_e32 v140, v152, v140
	v_mad_u32_u24 v102, v32, s89, v140
	v_and_b32_e32 v39, 15, v38
	ds_write_b128 v102, v[0:3]
	ds_write_b128 v102, v[4:7] offset:4608
	ds_write_b128 v102, v[8:11] offset:9216
	ds_write_b128 v102, v[12:15] offset:13824
	v_lshrrev_b32_e32 v0, 1, v38
	v_and_or_b32 v1, v0, s74, v39
	v_and_b32_e32 v0, 48, v38
	v_add_u32_e32 v141, 4, v38
	v_and_b32_e32 v141, 8, v141
	v_lshlrev_b32_e32 v141, 1, v141
	v_xor_b32_e32 v141, v0, v141
	v_mad_u32_u24 v104, v1, s89, v141
	v_and_b32_e32 v1, 0x4f, v38
	v_mul_u32_u24_e32 v1, 0x48, v1
	v_add_u32_e32 v142, 4, v33
	v_and_b32_e32 v142, 8, v142
	v_lshlrev_b32_e32 v142, 1, v142
	v_xor_b32_e32 v142, v152, v142
	v_xor_b32_e32 v143, 16, v142
	v_mad_u32_u24 v103, v33, s89, v142
	v_mad_u32_u24 v206, v33, s89, v143
	v_add_u32_e32 v207, 0x9000, v206
	v_lshl_add_u32 v105, v1, 1, v141
	v_mov_b32_e32 v0, 0
	s_mov_b64 s[82:83], 0x20080
	s_mov_b64 s[84:85], 0x30080
	v_add_u32_e32 v106, 0x9000, v103
	ds_write_b128 v103, v[16:19] offset:36864
	ds_write_b128 v206, v[20:23] offset:38016
	ds_write_b128 v103, v[24:27] offset:46080
	ds_write_b128 v206, v[28:31] offset:47232
	s_mov_b32 s19, 0
	s_movk_i32 s15, 0xc0
	v_mov_b32_e32 v1, v0
	v_mov_b32_e32 v2, v0
	v_mov_b32_e32 v3, v0
	v_mov_b32_e32 v4, v0
	v_mov_b32_e32 v5, v0
	v_mov_b32_e32 v6, v0
	v_mov_b32_e32 v7, v0
	v_mov_b32_e32 v8, v0
	v_mov_b32_e32 v9, v0
	v_mov_b32_e32 v10, v0
	v_mov_b32_e32 v11, v0
	v_mov_b32_e32 v12, v0
	v_mov_b32_e32 v13, v0
	v_mov_b32_e32 v14, v0
	v_mov_b32_e32 v15, v0
	v_mov_b32_e32 v16, v0
	v_mov_b32_e32 v17, v0
	v_mov_b32_e32 v18, v0
	v_mov_b32_e32 v19, v0
	v_mov_b32_e32 v20, v0
	v_mov_b32_e32 v21, v0
	v_mov_b32_e32 v22, v0
	v_mov_b32_e32 v23, v0
	v_mov_b32_e32 v24, v0
	v_mov_b32_e32 v25, v0
	v_mov_b32_e32 v26, v0
	v_mov_b32_e32 v27, v0
	v_mov_b32_e32 v28, v0
	v_mov_b32_e32 v29, v0
	v_mov_b32_e32 v30, v0
	v_mov_b32_e32 v31, v0
	v_mov_b32_e32 v32, v0
	v_mov_b32_e32 v33, v0
	v_mov_b32_e32 v34, v0
	v_mov_b32_e32 v35, v0
	v_mov_b32_e32 v36, v0
	v_mov_b32_e32 v37, v0
	v_mov_b32_e32 v38, v0
	v_mov_b32_e32 v39, v0
	v_mov_b32_e32 v68, v0
	v_mov_b32_e32 v69, v0
	v_mov_b32_e32 v70, v0
	v_mov_b32_e32 v71, v0
	v_mov_b32_e32 v76, v0
	v_mov_b32_e32 v77, v0
	v_mov_b32_e32 v78, v0
	v_mov_b32_e32 v79, v0
	v_mov_b32_e32 v80, v0
	v_mov_b32_e32 v81, v0
	v_mov_b32_e32 v82, v0
	v_mov_b32_e32 v83, v0
	v_mov_b32_e32 v84, v0
	v_mov_b32_e32 v85, v0
	v_mov_b32_e32 v86, v0
	v_mov_b32_e32 v87, v0
	v_mov_b32_e32 v88, v0
	v_mov_b32_e32 v89, v0
	v_mov_b32_e32 v90, v0
	v_mov_b32_e32 v91, v0
	v_mov_b32_e32 v92, v0
	v_mov_b32_e32 v93, v0
	v_mov_b32_e32 v94, v0
	v_mov_b32_e32 v95, v0
	s_waitcnt lgkmcnt(0)
	s_barrier
; template <int BN, bool SWAP> ...
;     ...
;   auto gl = [&](bf16x8 (&ra)[4], bf16x8 (&rb)[NJ], int kt) {
;     const bool nx = (kt >= nk);
;     const bfu* pa = nx ? (chain ? Apn + (kt - nk) * 64 : Ap + (nk - 1) * 64) : Ap + kt * 64;
;     const bfu* pb = nx ? (chain ? Bpn + (kt - nk) * 64 : Bp + (nk - 1) * 64) : Bp + kt * 64;
;     const size_t sa = (nx && chain) ? (size_t)ldan : (size_t)lda, sb = (nx && chain) ? (size_t)ldbn : (size_t)ldb;
; #pragma unroll
;     for (int q = 0; q < 4; ++q) ra[q] = gld16(pa + (size_t)(32 * q) * sa);
; #pragma unroll
;     for (int q = 0; q < NJ; ++q) rb[q] = gld16(pb + (size_t)(32 * q) * sb);
;   };
;   auto wt = [&](bf16x8 (&ra)[4], bf16x8 (&rb)[NJ]) {
;     if (NJ == 4) asm volatile("s_waitcnt vmcnt(8)" : "+v"(ra[0]), "+v"(ra[1]), "+v"(ra[2]), "+v"(ra[3]), "+v"(rb[0]), "+v"(rb[1]), "+v"(rb[NJ - 2]), "+v"(rb[NJ - 1]) : : "memory");
;     else asm volatile("s_waitcnt vmcnt(6)" : "+v"(ra[0]), "+v"(ra[1]), "+v"(ra[2]), "+v"(ra[3]), "+v"(rb[0]), "+v"(rb[1]) : : "memory");
;   };
;   auto st = [&](const bf16x8 (&ra)[4], const bf16x8 (&rb)[NJ], int buf) {
; #pragma unroll
;     for (int q = 0; q < 4; ++q) *(bf16x8*)(As + (buf * 128 + lrow + 32 * q) * 72 + lch) = ra[q];
; #pragma unroll
;     for (int q = 0; q < NJ; ++q) *(bf16x8*)(Bs + (buf * BN + brow + ((SWAP && NJ == 4) ? (8 * (q & 1) + 64 * (q >> 1)) : 32 * q)) * 72 + lch) = rb[q];
;   };
;   auto comp = [&](int buf, auto&& mid) {
;     const bfu* as = As + buf * 128 * 72 + (wr * 64 + c15) * 72 + g * 8;
;     const bfu* bs = Bs + buf * BN * 72 + (wc * (BN / 2) + c15) * 72 + g * 8;
;     {
;       bf16x8 a0[4], b0[NJ];
; #pragma unroll
;       for (int i = 0; i < 4; ++i) a0[i] = *(const bf16x8*)(as + i * 16 * 72);
; #pragma unroll
;       for (int j = 0; j < NJ; ++j) b0[j] = *(const bf16x8*)(bs + j * 16 * 72);
;       mid();
;       __builtin_amdgcn_s_setprio(1);
; #pragma unroll
;       for (int i = 0; i < 4; ++i)
; #pragma unroll
;         for (int j = 0; j < NJ; ++j) acc[i][j] = SWAP ? MFMA16(b0[j], a0[i], acc[i][j]) : MFMA16(a0[i], b0[j], acc[i][j]);
;       __builtin_amdgcn_s_setprio(0);
;     }
;     {
;       bf16x8 a1[4], b1[NJ];
; #pragma unroll
;       for (int i = 0; i < 4; ++i) a1[i] = *(const bf16x8*)(as + i * 16 * 72 + 32);
; #pragma unroll
;       for (int j = 0; j < NJ; ++j) b1[j] = *(const bf16x8*)(bs + j * 16 * 72 + 32);
;       __builtin_amdgcn_s_setprio(1);
.LBB0_485:
	s_add_i32 s20, s19, 2
	s_sub_i32 s2, s15, 64
	s_cmp_lt_u32 s19, 14
	s_cselect_b64 s[22:23], -1, 0
	s_and_b64 vcc, s[22:23], exec
	s_cselect_b32 s2, s2, 0x3c0
	s_lshl_b64 s[22:23], s[2:3], 1
	v_lshl_add_u64 v[120:121], v[98:99], 0, s[22:23]
	global_load_dwordx4 v[108:111], v[120:121], off
	v_lshl_add_u64 v[112:113], v[120:121], 0, s[76:77]
	global_load_dwordx4 v[112:115], v[112:113], off
	v_lshl_add_u64 v[116:117], v[120:121], 0, s[8:9]
	global_load_dwordx4 v[116:119], v[116:117], off
	v_lshl_add_u64 v[120:121], v[120:121], 0, s[78:79]
	v_lshl_add_u64 v[136:137], v[100:101], 0, s[22:23]
	global_load_dwordx4 v[120:123], v[120:121], off
	global_load_dwordx4 v[124:127], v[136:137], off
	v_lshl_add_u64 v[128:129], v[136:137], 0, s[76:77]
	global_load_dwordx4 v[128:131], v[128:129], off
	v_lshl_add_u64 v[132:133], v[136:137], 0, s[8:9]
	global_load_dwordx4 v[132:135], v[132:133], off
	v_lshl_add_u64 v[136:137], v[136:137], 0, s[78:79]
	global_load_dwordx4 v[136:139], v[136:137], off
	ds_read_b128 v[140:143], v104
	ds_read_b128 v[144:147], v104 offset:2304
	ds_read_b128 v[148:151], v104 offset:4608
	ds_read_b128 v[164:167], v104 offset:6912
	ds_read_b128 v[168:171], v105 offset:36864
	ds_read_b128 v[184:187], v105 offset:39168
	ds_read_b128 v[198:201], v105 offset:41472
	ds_read_b128 v[202:205], v105 offset:43776
	s_waitcnt vmcnt(8)
	ds_write_b128 v102, v[40:43] offset:18432
	ds_write_b128 v102, v[44:47] offset:23040
	ds_write_b128 v102, v[48:51] offset:27648
	ds_write_b128 v102, v[52:55] offset:32256
	ds_write_b128 v103, v[56:59] offset:55296
	ds_write_b128 v206, v[60:63] offset:56448
	ds_write_b128 v103, v[64:67] offset:64512
	ds_write_b128 v207, v[72:75] offset:28800
	s_setprio 1
	s_waitcnt lgkmcnt(11)
	v_mfma_f32_16x16x32_bf16 v[40:43], v[168:171], v[140:143], v[92:95]
	s_waitcnt lgkmcnt(10)
	v_mfma_f32_16x16x32_bf16 v[44:47], v[184:187], v[140:143], v[88:91]
	s_waitcnt lgkmcnt(9)
	v_mfma_f32_16x16x32_bf16 v[48:51], v[198:201], v[140:143], v[84:87]
	s_waitcnt lgkmcnt(8)
	v_mfma_f32_16x16x32_bf16 v[52:55], v[202:205], v[140:143], v[80:83]
	v_mfma_f32_16x16x32_bf16 v[56:59], v[168:171], v[144:147], v[76:79]
	v_mfma_f32_16x16x32_bf16 v[60:63], v[184:187], v[144:147], v[68:71]
	v_mfma_f32_16x16x32_bf16 v[36:39], v[198:201], v[144:147], v[36:39]
	v_mfma_f32_16x16x32_bf16 v[32:35], v[202:205], v[144:147], v[32:35]
	v_mfma_f32_16x16x32_bf16 v[28:31], v[168:171], v[148:151], v[28:31]
	v_mfma_f32_16x16x32_bf16 v[24:27], v[184:187], v[148:151], v[24:27]
	v_mfma_f32_16x16x32_bf16 v[20:23], v[198:201], v[148:151], v[20:23]
	v_mfma_f32_16x16x32_bf16 v[16:19], v[202:205], v[148:151], v[16:19]
	v_mfma_f32_16x16x32_bf16 v[12:15], v[168:171], v[164:167], v[12:15]
	v_mfma_f32_16x16x32_bf16 v[8:11], v[184:187], v[164:167], v[8:11]
	v_mfma_f32_16x16x32_bf16 v[4:7], v[198:201], v[164:167], v[4:7]
	v_mfma_f32_16x16x32_bf16 v[0:3], v[202:205], v[164:167], v[0:3]
	s_setprio 0
	ds_read_b128 v[64:67], v104 offset:64
	ds_read_b128 v[68:71], v104 offset:2368
	ds_read_b128 v[72:75], v104 offset:4672
	ds_read_b128 v[76:79], v104 offset:6976
	ds_read_b128 v[80:83], v105 offset:36928
	ds_read_b128 v[84:87], v105 offset:39232
	ds_read_b128 v[88:91], v105 offset:41536
	ds_read_b128 v[92:95], v105 offset:43840
	s_setprio 1
	s_waitcnt lgkmcnt(1)
	v_mfma_f32_16x16x32_bf16 v[36:39], v[88:91], v[68:71], v[36:39]
	s_waitcnt lgkmcnt(0)
	v_mfma_f32_16x16x32_bf16 v[32:35], v[92:95], v[68:71], v[32:35]
	v_mfma_f32_16x16x32_bf16 v[28:31], v[80:83], v[72:75], v[28:31]
	v_mfma_f32_16x16x32_bf16 v[24:27], v[84:87], v[72:75], v[24:27]
	v_mfma_f32_16x16x32_bf16 v[20:23], v[88:91], v[72:75], v[20:23]
	v_mfma_f32_16x16x32_bf16 v[16:19], v[92:95], v[72:75], v[16:19]
	v_mfma_f32_16x16x32_bf16 v[12:15], v[80:83], v[76:79], v[12:15]
	v_mfma_f32_16x16x32_bf16 v[8:11], v[84:87], v[76:79], v[8:11]
	v_mfma_f32_16x16x32_bf16 v[4:7], v[88:91], v[76:79], v[4:7]
	v_mfma_f32_16x16x32_bf16 v[0:3], v[92:95], v[76:79], v[0:3]
	v_mfma_f32_16x16x32_bf16 v[140:143], v[80:83], v[64:67], v[40:43]
	v_mfma_f32_16x16x32_bf16 v[144:147], v[84:87], v[64:67], v[44:47]
	v_mfma_f32_16x16x32_bf16 v[148:151], v[88:91], v[64:67], v[48:51]
	v_mfma_f32_16x16x32_bf16 v[164:167], v[92:95], v[64:67], v[52:55]
	v_mfma_f32_16x16x32_bf16 v[168:171], v[80:83], v[68:71], v[56:59]
	v_mfma_f32_16x16x32_bf16 v[184:187], v[84:87], v[68:71], v[60:63]
	s_setprio 0
	s_cmp_lt_u32 s19, 13
	s_cselect_b32 s2, s15, 0x3c0
	s_lshl_b64 s[22:23], s[2:3], 1
	v_lshl_add_u64 v[52:53], v[98:99], 0, s[22:23]
	s_barrier
; template <int BN, bool SWAP> ...
;     ...
;   auto st = [&](const bf16x8 (&ra)[4], const bf16x8 (&rb)[NJ], int buf) {
; #pragma unroll
;     for (int q = 0; q < 4; ++q) *(bf16x8*)(As + (buf * 128 + lrow + 32 * q) * 72 + lch) = ra[q];
; #pragma unroll
;     for (int q = 0; q < NJ; ++q) *(bf16x8*)(Bs + (buf * BN + brow + ((SWAP && NJ == 4) ? (8 * (q & 1) + 64 * (q >> 1)) : 32 * q)) * 72 + lch) = rb[q];
;   };
;   auto comp = [&](int buf, auto&& mid) {
;     const bfu* as = As + buf * 128 * 72 + (wr * 64 + c15) * 72 + g * 8;
;     const bfu* bs = Bs + buf * BN * 72 + (wc * (BN / 2) + c15) * 72 + g * 8;
;     {
;       bf16x8 a0[4], b0[NJ];
; #pragma unroll
;       for (int i = 0; i < 4; ++i) a0[i] = *(const bf16x8*)(as + i * 16 * 72);
; #pragma unroll
;       for (int j = 0; j < NJ; ++j) b0[j] = *(const bf16x8*)(bs + j * 16 * 72);
;       mid();
;       __builtin_amdgcn_s_setprio(1);
; #pragma unroll
;       for (int i = 0; i < 4; ++i)
; #pragma unroll
;         for (int j = 0; j < NJ; ++j) acc[i][j] = SWAP ? MFMA16(b0[j], a0[i], acc[i][j]) : MFMA16(a0[i], b0[j], acc[i][j]);
;       __builtin_amdgcn_s_setprio(0);
;     }
;     {
;       bf16x8 a1[4], b1[NJ];
; #pragma unroll
;       for (int i = 0; i < 4; ++i) a1[i] = *(const bf16x8*)(as + i * 16 * 72 + 32);
; #pragma unroll
;       for (int j = 0; j < NJ; ++j) b1[j] = *(const bf16x8*)(bs + j * 16 * 72 + 32);
;       __builtin_amdgcn_s_setprio(1);
; #pragma unroll
;       for (int i = 0; i < 4; ++i)
; #pragma unroll
;         for (int j = 0; j < NJ; ++j) acc[i][j] = SWAP ? MFMA16(b1[j], a1[i], acc[i][j]) : MFMA16(a1[i], b1[j], acc[i][j]);
;       __builtin_amdgcn_s_setprio(0);
;     }
; template <int G>
; __device__ __forceinline__ void p5(const Params& P, const Ptrs<G>& w, int pass, int layer, bfu* sm, const XcdInfo& xi) {
;     ...
;     const size_t eb = (size_t)(m0 + wr * 64 + c15) * 1024 + n0 + wc * 64 + 16 * g;
; #pragma unroll
;     for (int i = 0; i < 4; ++i) {
;       const size_t e = eb + (size_t)(16 * i) * 1024;
;       unsigned pk[8];
; #pragma unroll
;       for (int j = 0; j < 4; ++j) {
;         const float4 x0 = *(const float4*)(xres + e + 4 * j);
;         float4 v;
;         v.x = ALPHA_DN * x0.x + C[i][j][0]; v.y = ALPHA_DN * x0.y + C[i][j][1]; v.z = ALPHA_DN * x0.z + C[i][j][2]; v.w = ALPHA_DN * x0.w + C[i][j][3];
;         *(float4*)(w.r() + e + 4 * j) = v;
	global_load_dwordx4 v[40:43], v[52:53], off
	v_lshl_add_u64 v[44:45], v[52:53], 0, s[76:77]
	global_load_dwordx4 v[44:47], v[44:45], off
	v_lshl_add_u64 v[48:49], v[52:53], 0, s[8:9]
	global_load_dwordx4 v[48:51], v[48:49], off
	v_lshl_add_u64 v[52:53], v[52:53], 0, s[78:79]
	v_lshl_add_u64 v[68:69], v[100:101], 0, s[22:23]
	global_load_dwordx4 v[52:55], v[52:53], off
	global_load_dwordx4 v[56:59], v[68:69], off
	v_lshl_add_u64 v[60:61], v[68:69], 0, s[76:77]
	global_load_dwordx4 v[60:63], v[60:61], off
	v_lshl_add_u64 v[64:65], v[68:69], 0, s[8:9]
	global_load_dwordx4 v[64:67], v[64:65], off
	v_lshl_add_u64 v[68:69], v[68:69], 0, s[78:79]
	global_load_dwordx4 v[72:75], v[68:69], off
	ds_read_b128 v[68:71], v104 offset:18432
	ds_read_b128 v[76:79], v104 offset:20736
	ds_read_b128 v[80:83], v104 offset:23040
	ds_read_b128 v[84:87], v104 offset:25344
	ds_read_b128 v[88:91], v105 offset:55296
	ds_read_b128 v[92:95], v105 offset:57600
	ds_read_b128 v[198:201], v105 offset:59904
	ds_read_b128 v[202:205], v105 offset:62208
	s_waitcnt vmcnt(8)
	ds_write_b128 v102, v[108:111]
	ds_write_b128 v102, v[112:115] offset:4608
	ds_write_b128 v102, v[116:119] offset:9216
	ds_write_b128 v102, v[120:123] offset:13824
	ds_write_b128 v103, v[124:127] offset:36864
	ds_write_b128 v206, v[128:131] offset:38016
	ds_write_b128 v103, v[132:135] offset:46080
	ds_write_b128 v206, v[136:139] offset:47232
	s_setprio 1
	s_waitcnt lgkmcnt(11)
	v_mfma_f32_16x16x32_bf16 v[108:111], v[88:91], v[68:71], v[140:143]
	s_waitcnt lgkmcnt(10)
	v_mfma_f32_16x16x32_bf16 v[112:115], v[92:95], v[68:71], v[144:147]
	s_waitcnt lgkmcnt(9)
	v_mfma_f32_16x16x32_bf16 v[116:119], v[198:201], v[68:71], v[148:151]
	s_waitcnt lgkmcnt(8)
	v_mfma_f32_16x16x32_bf16 v[68:71], v[202:205], v[68:71], v[164:167]
	v_mfma_f32_16x16x32_bf16 v[36:39], v[198:201], v[76:79], v[36:39]
	v_mfma_f32_16x16x32_bf16 v[32:35], v[202:205], v[76:79], v[32:35]
	v_mfma_f32_16x16x32_bf16 v[28:31], v[88:91], v[80:83], v[28:31]
	v_mfma_f32_16x16x32_bf16 v[24:27], v[92:95], v[80:83], v[24:27]
	v_mfma_f32_16x16x32_bf16 v[20:23], v[198:201], v[80:83], v[20:23]
	v_mfma_f32_16x16x32_bf16 v[16:19], v[202:205], v[80:83], v[16:19]
	v_mfma_f32_16x16x32_bf16 v[12:15], v[88:91], v[84:87], v[12:15]
	v_mfma_f32_16x16x32_bf16 v[8:11], v[92:95], v[84:87], v[8:11]
	v_mfma_f32_16x16x32_bf16 v[4:7], v[198:201], v[84:87], v[4:7]
	v_mfma_f32_16x16x32_bf16 v[0:3], v[202:205], v[84:87], v[0:3]
	v_mfma_f32_16x16x32_bf16 v[120:123], v[88:91], v[76:79], v[168:171]
	v_mfma_f32_16x16x32_bf16 v[124:127], v[92:95], v[76:79], v[184:187]
	s_setprio 0
	ds_read_b128 v[76:79], v104 offset:18496
	ds_read_b128 v[128:131], v104 offset:20800
	ds_read_b128 v[132:135], v104 offset:23104
	ds_read_b128 v[136:139], v104 offset:25408
	ds_read_b128 v[140:143], v105 offset:55360
	ds_read_b128 v[144:147], v105 offset:57664
	ds_read_b128 v[148:151], v105 offset:59968
	ds_read_b128 v[164:167], v105 offset:62272
	s_setprio 1
	s_waitcnt lgkmcnt(3)
	v_mfma_f32_16x16x32_bf16 v[92:95], v[140:143], v[76:79], v[108:111]
	s_waitcnt lgkmcnt(2)
	v_mfma_f32_16x16x32_bf16 v[88:91], v[144:147], v[76:79], v[112:115]
	s_waitcnt lgkmcnt(1)
	v_mfma_f32_16x16x32_bf16 v[84:87], v[148:151], v[76:79], v[116:119]
	s_waitcnt lgkmcnt(0)
	v_mfma_f32_16x16x32_bf16 v[80:83], v[164:167], v[76:79], v[68:71]
	v_mfma_f32_16x16x32_bf16 v[76:79], v[140:143], v[128:131], v[120:123]
	v_mfma_f32_16x16x32_bf16 v[68:71], v[144:147], v[128:131], v[124:127]
	v_mfma_f32_16x16x32_bf16 v[36:39], v[148:151], v[128:131], v[36:39]
	v_mfma_f32_16x16x32_bf16 v[32:35], v[164:167], v[128:131], v[32:35]
	v_mfma_f32_16x16x32_bf16 v[28:31], v[140:143], v[132:135], v[28:31]
	v_mfma_f32_16x16x32_bf16 v[24:27], v[144:147], v[132:135], v[24:27]
	v_mfma_f32_16x16x32_bf16 v[20:23], v[148:151], v[132:135], v[20:23]
	v_mfma_f32_16x16x32_bf16 v[16:19], v[164:167], v[132:135], v[16:19]
	v_mfma_f32_16x16x32_bf16 v[12:15], v[140:143], v[136:139], v[12:15]
	v_mfma_f32_16x16x32_bf16 v[8:11], v[144:147], v[136:139], v[8:11]
	v_mfma_f32_16x16x32_bf16 v[4:7], v[148:151], v[136:139], v[4:7]
	v_mfma_f32_16x16x32_bf16 v[0:3], v[164:167], v[136:139], v[0:3]
	s_setprio 0
	s_addk_i32 s15, 0x80
	s_mov_b32 s19, s20
	s_barrier
	s_cbranch_vccnz .LBB0_485
	s_waitcnt vmcnt(0)
	s_mov_b32 s20, 0x3fb504f3
	v_add_u32_e32 v40, s14, v97
	v_ashrrev_i32_e32 v41, 31, v40
	v_lshlrev_b64 v[40:41], 10, v[40:41]
	v_mov_b32_e32 v43, s13
	v_or_b32_e32 v42, s12, v96
	v_lshl_add_u64 v[40:41], v[40:41], 0, v[42:43]
	v_lshlrev_b64 v[44:45], 2, v[40:41]
	v_lshl_add_u64 v[46:47], s[0:1], 0, v[44:45]
	global_load_dwordx4 v[48:51], v[46:47], off
	v_lshl_add_u64 v[42:43], s[66:67], 0, v[44:45]
	v_readlane_b32 s12, v253, 38
	v_readlane_b32 s14, v253, 40
	v_readlane_b32 s15, v253, 41
	s_mov_b32 s2, 0x14121000
	v_readlane_b32 s13, v253, 39
	v_lshl_add_u64 v[44:45], s[14:15], 0, v[44:45]
	v_add_co_u32_e32 v72, vcc, s2, v44
	v_readlane_b32 s12, v252, 38
	s_nop 0
	v_addc_co_u32_e32 v73, vcc, 0, v45, vcc
	v_readlane_b32 s13, v252, 39
	s_waitcnt vmcnt(0)
	v_pk_fma_f32 v[48:49], v[48:49], s[20:21], v[92:93] op_sel_hi:[1,0,1]
	v_pk_fma_f32 v[50:51], v[50:51], s[20:21], v[94:95] op_sel_hi:[1,0,1]
	global_store_dwordx4 v[42:43], v[48:51], off
	global_load_dwordx4 v[52:55], v[46:47], off offset:16
	v_lshl_add_u64 v[40:41], v[40:41], 1, s[12:13]
	v_cvt_pk_bf16_f32 v65, v50, v51
	v_cvt_pk_bf16_f32 v64, v48, v49
	s_waitcnt vmcnt(0)
	v_pk_fma_f32 v[52:53], v[52:53], s[20:21], v[88:89] op_sel_hi:[1,0,1]
	v_pk_fma_f32 v[54:55], v[54:55], s[20:21], v[90:91] op_sel_hi:[1,0,1]
	global_store_dwordx4 v[72:73], v[52:55], off offset:2064
	global_load_dwordx4 v[56:59], v[46:47], off offset:32
	v_cvt_pk_bf16_f32 v67, v54, v55
	v_cvt_pk_bf16_f32 v66, v52, v53
	s_waitcnt vmcnt(0)
;   __device__ __forceinline__ bfu* rb() const { return (bfu*)(b + L::o_rb); }
;   __device__ __forceinline__ float* r() const { return (float*)(b + L::o_r); }
; template <int G>
; __device__ __forceinline__ void p5(const Params& P, const Ptrs<G>& w, int pass, int layer, bfu* sm, const XcdInfo& xi) {
;     ...
;     const size_t eb = (size_t)(m0 + wr * 64 + c15) * 1024 + n0 + wc * 64 + 16 * g;
; #pragma unroll
;     for (int i = 0; i < 4; ++i) {
;       const size_t e = eb + (size_t)(16 * i) * 1024;
;       unsigned pk[8];
; #pragma unroll
;       for (int j = 0; j < 4; ++j) {
;         const float4 x0 = *(const float4*)(xres + e + 4 * j);
;         float4 v;
;         v.x = ALPHA_DN * x0.x + C[i][j][0]; v.y = ALPHA_DN * x0.y + C[i][j][1]; v.z = ALPHA_DN * x0.z + C[i][j][2]; v.w = ALPHA_DN * x0.w + C[i][j][3];
;         *(float4*)(w.r() + e + 4 * j) = v;
;         pk[2 * j] = pack2(v.x, v.y); pk[2 * j + 1] = pack2(v.z, v.w);
;       }
;       *(uint4*)(w.rb() + e) = make_uint4(pk[0], pk[1], pk[2], pk[3]);
;       *(uint4*)(w.rb() + e + 8) = make_uint4(pk[4], pk[5], pk[6], pk[7]);
;       __builtin_amdgcn_sched_barrier(0);
;     }
;   }
	v_pk_fma_f32 v[56:57], v[56:57], s[20:21], v[84:85] op_sel_hi:[1,0,1]
	v_pk_fma_f32 v[58:59], v[58:59], s[20:21], v[86:87] op_sel_hi:[1,0,1]
	global_store_dwordx4 v[72:73], v[56:59], off offset:2080
	global_load_dwordx4 v[60:63], v[46:47], off offset:48
	v_cvt_pk_bf16_f32 v49, v58, v59
	v_cvt_pk_bf16_f32 v48, v56, v57
	s_waitcnt vmcnt(0)
	v_pk_fma_f32 v[52:53], v[60:61], s[20:21], v[80:81] op_sel_hi:[1,0,1]
	v_pk_fma_f32 v[54:55], v[62:63], s[20:21], v[82:83] op_sel_hi:[1,0,1]
	v_cvt_pk_bf16_f32 v50, v52, v53
	v_cvt_pk_bf16_f32 v51, v54, v55
	global_store_dwordx4 v[72:73], v[52:55], off offset:2096
	global_store_dwordx4 v[40:41], v[64:67], off
	global_store_dwordx4 v[40:41], v[48:51], off offset:16
	s_mov_b32 s12, 0x10000
	s_nop 0
	v_add_co_u32_e32 v48, vcc, s12, v46
	v_lshl_add_u64 v[60:61], v[46:47], 0, s[76:77]
	s_nop 0
	v_addc_co_u32_e32 v49, vcc, 0, v47, vcc
	global_load_dwordx4 v[48:51], v[48:49], off
	v_add_co_u32_e32 v52, vcc, s12, v42
	s_mov_b32 s2, 0x14131000
	s_nop 0
	v_addc_co_u32_e32 v53, vcc, 0, v43, vcc
	v_add_co_u32_e32 v62, vcc, s2, v44
	s_waitcnt vmcnt(0)
	v_pk_fma_f32 v[48:49], v[48:49], s[20:21], v[76:77] op_sel_hi:[1,0,1]
	v_pk_fma_f32 v[50:51], v[50:51], s[20:21], v[78:79] op_sel_hi:[1,0,1]
	global_store_dwordx4 v[52:53], v[48:51], off
	global_load_dwordx4 v[52:55], v[60:61], off offset:16
	v_addc_co_u32_e32 v63, vcc, 0, v45, vcc
	s_waitcnt vmcnt(0)
	v_pk_fma_f32 v[52:53], v[52:53], s[20:21], v[68:69] op_sel_hi:[1,0,1]
	v_pk_fma_f32 v[54:55], v[54:55], s[20:21], v[70:71] op_sel_hi:[1,0,1]
	global_store_dwordx4 v[62:63], v[52:55], off offset:2064
	global_load_dwordx4 v[56:59], v[60:61], off offset:32
	s_waitcnt vmcnt(0)
	v_pk_fma_f32 v[36:37], v[56:57], s[20:21], v[36:37] op_sel_hi:[1,0,1]
	v_pk_fma_f32 v[38:39], v[58:59], s[20:21], v[38:39] op_sel_hi:[1,0,1]
	global_store_dwordx4 v[62:63], v[36:39], off offset:2080
	global_load_dwordx4 v[56:59], v[60:61], off offset:48
	v_lshl_add_u64 v[60:61], v[40:41], 0, s[6:7]
	s_waitcnt vmcnt(0)
	v_pk_fma_f32 v[32:33], v[56:57], s[20:21], v[32:33] op_sel_hi:[1,0,1]
	v_cvt_pk_bf16_f32 v56, v48, v49
	v_add_co_u32_e32 v48, vcc, s88, v40
	v_pk_fma_f32 v[34:35], v[58:59], s[20:21], v[34:35] op_sel_hi:[1,0,1]
	v_cvt_pk_bf16_f32 v57, v50, v51
	v_cvt_pk_bf16_f32 v59, v54, v55
	v_cvt_pk_bf16_f32 v58, v52, v53
	v_addc_co_u32_e32 v49, vcc, 0, v41, vcc
	global_store_dwordx4 v[62:63], v[32:35], off offset:2096
	global_store_dwordx4 v[48:49], v[56:59], off
	v_cvt_pk_bf16_f32 v49, v38, v39
	v_cvt_pk_bf16_f32 v51, v34, v35
	v_cvt_pk_bf16_f32 v48, v36, v37
	v_cvt_pk_bf16_f32 v50, v32, v33
	global_store_dwordx4 v[60:61], v[48:51], off offset:16
	s_mov_b32 s2, 0x20000
	v_add_co_u32_e32 v32, vcc, s2, v46
	v_lshl_add_u64 v[36:37], v[46:47], 0, s[8:9]
	s_nop 0
	v_addc_co_u32_e32 v33, vcc, 0, v47, vcc
	global_load_dwordx4 v[32:35], v[32:33], off
	s_mov_b32 s7, 0x20000
	s_waitcnt vmcnt(0)
	v_pk_fma_f32 v[28:29], v[32:33], s[20:21], v[28:29] op_sel_hi:[1,0,1]
	v_add_co_u32_e32 v32, vcc, s2, v42
	v_pk_fma_f32 v[30:31], v[34:35], s[20:21], v[30:31] op_sel_hi:[1,0,1]
	s_nop 0
	v_addc_co_u32_e32 v33, vcc, 0, v43, vcc
	global_store_dwordx4 v[32:33], v[28:31], off
	global_load_dwordx4 v[32:35], v[36:37], off offset:16
	s_mov_b32 s2, 0x14141000
	v_add_co_u32_e32 v38, vcc, s2, v44
	v_cvt_pk_bf16_f32 v31, v30, v31
	s_nop 0
	v_addc_co_u32_e32 v39, vcc, 0, v45, vcc
	v_cvt_pk_bf16_f32 v30, v28, v29
	s_waitcnt vmcnt(0)
	v_pk_fma_f32 v[24:25], v[32:33], s[20:21], v[24:25] op_sel_hi:[1,0,1]
	v_pk_fma_f32 v[26:27], v[34:35], s[20:21], v[26:27] op_sel_hi:[1,0,1]
	global_store_dwordx4 v[38:39], v[24:27], off offset:2064
	global_load_dwordx4 v[32:35], v[36:37], off offset:32
	s_waitcnt vmcnt(0)
	v_pk_fma_f32 v[20:21], v[32:33], s[20:21], v[20:21] op_sel_hi:[1,0,1]
	v_pk_fma_f32 v[22:23], v[34:35], s[20:21], v[22:23] op_sel_hi:[1,0,1]
	global_store_dwordx4 v[38:39], v[20:23], off offset:2080
	global_load_dwordx4 v[32:35], v[36:37], off offset:48
	s_waitcnt vmcnt(0)
	v_pk_fma_f32 v[16:17], v[32:33], s[20:21], v[16:17] op_sel_hi:[1,0,1]
	v_cvt_pk_bf16_f32 v32, v24, v25
	v_add_co_u32_e32 v24, vcc, s12, v40
	v_pk_fma_f32 v[18:19], v[34:35], s[20:21], v[18:19] op_sel_hi:[1,0,1]
	v_cvt_pk_bf16_f32 v33, v26, v27
	v_addc_co_u32_e32 v25, vcc, 0, v41, vcc
	global_store_dwordx4 v[38:39], v[16:19], off offset:2096
	v_lshl_add_u64 v[34:35], v[40:41], 0, s[76:77]
	global_store_dwordx4 v[24:25], v[30:33], off
	v_cvt_pk_bf16_f32 v23, v22, v23
	v_cvt_pk_bf16_f32 v25, v18, v19
	v_cvt_pk_bf16_f32 v22, v20, v21
	v_cvt_pk_bf16_f32 v24, v16, v17
	global_store_dwordx4 v[34:35], v[22:25], off offset:16
	v_add_co_u32_e32 v16, vcc, s75, v46
	v_lshl_add_u64 v[20:21], v[46:47], 0, s[78:79]
	s_nop 0
	v_addc_co_u32_e32 v17, vcc, 0, v47, vcc
	global_load_dwordx4 v[16:19], v[16:17], off
	v_add_co_u32_e32 v22, vcc, s75, v42
	s_mov_b32 s2, 0x14151000
	s_nop 0
	v_addc_co_u32_e32 v23, vcc, 0, v43, vcc
	v_add_co_u32_e32 v24, vcc, s2, v44
	s_mov_b64 s[12:13], 0x18000
	s_nop 0
	v_addc_co_u32_e32 v25, vcc, 0, v45, vcc
	s_mov_b32 s2, 0x18000
	v_lshl_add_u64 v[26:27], v[40:41], 0, s[12:13]
	v_add_co_u32_e32 v28, vcc, s2, v40
	s_waitcnt vmcnt(0)
	v_pk_fma_f32 v[12:13], v[16:17], s[20:21], v[12:13] op_sel_hi:[1,0,1]
	v_pk_fma_f32 v[14:15], v[18:19], s[20:21], v[14:15] op_sel_hi:[1,0,1]
	global_store_dwordx4 v[22:23], v[12:15], off
	global_load_dwordx4 v[16:19], v[20:21], off offset:16
	v_addc_co_u32_e32 v29, vcc, 0, v41, vcc
	s_waitcnt vmcnt(0)
	v_pk_fma_f32 v[8:9], v[16:17], s[20:21], v[8:9] op_sel_hi:[1,0,1]
	v_pk_fma_f32 v[10:11], v[18:19], s[20:21], v[10:11] op_sel_hi:[1,0,1]
	global_store_dwordx4 v[24:25], v[8:11], off offset:2064
	global_load_dwordx4 v[16:19], v[20:21], off offset:32
	v_cvt_pk_bf16_f32 v22, v8, v9
	v_cvt_pk_bf16_f32 v23, v10, v11
	s_waitcnt vmcnt(0)
	v_pk_fma_f32 v[4:5], v[16:17], s[20:21], v[4:5] op_sel_hi:[1,0,1]
	v_pk_fma_f32 v[6:7], v[18:19], s[20:21], v[6:7] op_sel_hi:[1,0,1]
	global_store_dwordx4 v[24:25], v[4:7], off offset:2080
	global_load_dwordx4 v[16:19], v[20:21], off offset:48
	v_cvt_pk_bf16_f32 v21, v14, v15
	v_cvt_pk_bf16_f32 v7, v6, v7
	v_cvt_pk_bf16_f32 v6, v4, v5
	v_cvt_pk_bf16_f32 v20, v12, v13
	s_waitcnt vmcnt(0)
	v_pk_fma_f32 v[0:1], v[16:17], s[20:21], v[0:1] op_sel_hi:[1,0,1]
	v_pk_fma_f32 v[2:3], v[18:19], s[20:21], v[2:3] op_sel_hi:[1,0,1]
	v_cvt_pk_bf16_f32 v8, v0, v1
	v_cvt_pk_bf16_f32 v9, v2, v3
	global_store_dwordx4 v[24:25], v[0:3], off offset:2096
	global_store_dwordx4 v[28:29], v[20:23], off
	global_store_dwordx4 v[26:27], v[6:9], off offset:16
	v_readlane_b32 s2, v254, 27
	s_add_i32 s18, s18, s2
	v_readlane_b32 s2, v254, 34
	s_cmp_lt_i32 s18, s2
	s_cbranch_scc1 .LBB0_480
	v_readlane_b32 s6, v254, 49
